# speedup vs baseline: 1.0048x; 1.0048x over previous
; DI int bid_() { int b = blockIdx.x; asm volatile("" : "+s"(b)); return b; }
; DI void phase_final_norm(float* x, const float* g, int rows) {
;     ...
;   for (int row = bid_() * 8 + wid; row < rows; row += gridDim.x * 8) {
;     float* xr = x + (size_t)row * 1024;
;     float4 v[4]; float ss = 0.f;
; #pragma unroll
;     for (int i = 0; i < 4; ++i) { float4 t = *reinterpret_cast<const float4*>(xr + i * 256 + lane * 4); v[i] = t; ss += t.x * t.x + t.y * t.y + t.z * t.z + t.w * t.w; }
;     ss = wave_sum_l(ss, lane);
;     const float r = rsqrtf(ss * (1.f / 1024.f) + EPS);
; #pragma unroll
;     for (int i = 0; i < 4; ++i) { const float4 gg = *reinterpret_cast<const float4*>(g + i * 256 + lane * 4);
;       float4 o = make_float4(v[i].x * r * gg.x, v[i].y * r * gg.y, v[i].z * r * gg.z, v[i].w * r * gg.w);
;       *reinterpret_cast<float4*>(xr + i * 256 + lane * 4) = o; }
;   }
.LBB0_32:
	v_ashrrev_i32_e32 v1, 31, v0
	v_lshlrev_b64 v[8:9], 12, v[0:1]
	v_lshl_add_u64 v[28:29], v[4:5], 0, v[8:9]
	global_load_dwordx4 v[8:11], v[28:29], off
	global_load_dwordx4 v[12:15], v[28:29], off offset:1024
	global_load_dwordx4 v[16:19], v[28:29], off offset:2048
	global_load_dwordx4 v[20:23], v[28:29], off offset:3072
	v_add_u32_e32 v0, s99, v0
	s_mov_b32 s2, 0xbfff
	s_waitcnt vmcnt(3)
	v_mov_b32_e32 v32, v9
	s_waitcnt vmcnt(2)
	v_mov_b32_e32 v33, v13
	v_mov_b32_e32 v30, v8
	v_mov_b32_e32 v31, v12
	s_waitcnt vmcnt(1)
	v_mov_b32_e32 v40, v17
	s_waitcnt vmcnt(0)
	v_mov_b32_e32 v41, v21
	v_pk_mul_f32 v[32:33], v[32:33], v[32:33]
	v_mov_b32_e32 v34, v10
	v_mov_b32_e32 v35, v14
	v_mov_b32_e32 v38, v16
	v_mov_b32_e32 v39, v20
	v_pk_mul_f32 v[40:41], v[40:41], v[40:41]
	v_pk_fma_f32 v[30:31], v[30:31], v[30:31], v[32:33]
	v_mov_b32_e32 v36, v11
	v_mov_b32_e32 v37, v15
	v_mov_b32_e32 v42, v18
	v_mov_b32_e32 v43, v22
	v_pk_fma_f32 v[32:33], v[38:39], v[38:39], v[40:41]
	v_pk_fma_f32 v[30:31], v[34:35], v[34:35], v[30:31]
	v_mov_b32_e32 v44, v19
	v_mov_b32_e32 v45, v23
	v_pk_fma_f32 v[32:33], v[42:43], v[42:43], v[32:33]
	v_pk_fma_f32 v[30:31], v[36:37], v[36:37], v[30:31]
	v_pk_fma_f32 v[32:33], v[44:45], v[44:45], v[32:33]
	v_add_f32_e32 v1, v30, v31
	v_add_f32_e32 v1, v1, v32
	v_add_f32_e32 v1, v1, v33
	s_nop 1
	v_add_f32_dpp v1, v1, v1 quad_perm:[1,0,3,2] row_mask:0xf bank_mask:0xf bound_ctrl:1
	s_nop 1
	v_add_f32_dpp v1, v1, v1 quad_perm:[2,3,0,1] row_mask:0xf bank_mask:0xf bound_ctrl:1
	s_nop 1
	v_add_f32_dpp v1, v1, v1 row_half_mirror row_mask:0xf bank_mask:0xf bound_ctrl:1
	s_nop 1
	v_add_f32_dpp v1, v1, v1 row_mirror row_mask:0xf bank_mask:0xf bound_ctrl:1
	ds_bpermute_b32 v30, v6, v1
	s_waitcnt lgkmcnt(0)
	v_add_f32_e32 v1, v1, v30
	ds_bpermute_b32 v30, v7, v1
	s_waitcnt lgkmcnt(0)
	v_add_f32_e32 v1, v1, v30
	v_fmamk_f32 v1, v1, 0x3a800000, v233
	v_mul_f32_e32 v30, 0x4b800000, v1
	v_cmp_gt_f32_e32 vcc, s94, v1
	s_nop 1
	v_cndmask_b32_e32 v1, v1, v30, vcc
	v_rsq_f32_e32 v1, v1
	s_nop 0
	v_mul_f32_e32 v30, 0x45800000, v1
	v_cndmask_b32_e32 v30, v1, v30, vcc
	v_pk_mul_f32 v[8:9], v[8:9], v[30:31] op_sel_hi:[1,0]
	v_pk_mul_f32 v[10:11], v[10:11], v[30:31] op_sel_hi:[1,0]
	v_pk_mul_f32 v[8:9], v[48:49], v[8:9]
	v_pk_mul_f32 v[10:11], v[50:51], v[10:11]
	global_store_dwordx4 v[28:29], v[8:11], off nt
	v_pk_mul_f32 v[12:13], v[12:13], v[30:31] op_sel_hi:[1,0]
	v_pk_mul_f32 v[14:15], v[14:15], v[30:31] op_sel_hi:[1,0]
	v_cmp_lt_i32_e32 vcc, s2, v0
	s_or_b64 s[36:37], vcc, s[36:37]
	v_pk_mul_f32 v[12:13], v[52:53], v[12:13]
	v_pk_mul_f32 v[14:15], v[54:55], v[14:15]
	global_store_dwordx4 v[28:29], v[12:15], off offset:1024 nt
	v_pk_mul_f32 v[16:17], v[16:17], v[30:31] op_sel_hi:[1,0]
	v_pk_mul_f32 v[18:19], v[18:19], v[30:31] op_sel_hi:[1,0]
	v_pk_mul_f32 v[16:17], v[16:17], v[56:57]
	v_pk_mul_f32 v[18:19], v[18:19], v[58:59]
	global_store_dwordx4 v[28:29], v[16:19], off offset:2048 nt
	v_pk_mul_f32 v[20:21], v[20:21], v[30:31] op_sel_hi:[1,0]
	v_pk_mul_f32 v[22:23], v[22:23], v[30:31] op_sel_hi:[1,0]
	v_pk_mul_f32 v[20:21], v[20:21], v[60:61]
	v_pk_mul_f32 v[22:23], v[22:23], v[62:63]
	global_store_dwordx4 v[28:29], v[20:23], off offset:3072 nt
	s_andn2_b64 exec, exec, s[36:37]
	s_cbranch_execnz .LBB0_32
